# B3 row loop: 16-lane sum via four DPP row_ror adds (same operand order) instead of four ds_bpermute round trips (on v028)
# baseline (speedup 1.0000x reference)
; DI unsigned pack2(float a, float b) { hwf2 v = {a, b}; hwbf2 r = __builtin_convertvector(v, hwbf2); return __builtin_bit_cast(unsigned, r); }
; DI void phaseB3(const Params& p, int l) {
;     ...
;   for (; t < T_TOK; t += tstep) {
;     const uint4 ov = nov, zv = nzv;
;     const int tn = t + tstep < T_TOK ? t + tstep : t;
;     nov = *(const uint4*)(p.ob + (size_t)tn * 512 + lane * 8); nzv = *(const uint4*)(p.projZ + (size_t)tn * LDA_Z + 256 + lane * 8);
;     float v[8], z[8];
;     v[0] = __uint_as_float(ov.x << 16); v[1] = __uint_as_float(ov.x & 0xffff0000u);
;     v[2] = __uint_as_float(ov.y << 16); v[3] = __uint_as_float(ov.y & 0xffff0000u);
;     v[4] = __uint_as_float(ov.z << 16); v[5] = __uint_as_float(ov.z & 0xffff0000u);
;     v[6] = __uint_as_float(ov.w << 16); v[7] = __uint_as_float(ov.w & 0xffff0000u);
;     z[0] = __uint_as_float(zv.x << 16); z[1] = __uint_as_float(zv.x & 0xffff0000u);
;     z[2] = __uint_as_float(zv.y << 16); z[3] = __uint_as_float(zv.y & 0xffff0000u);
;     z[4] = __uint_as_float(zv.z << 16); z[5] = __uint_as_float(zv.z & 0xffff0000u);
;     z[6] = __uint_as_float(zv.w << 16); z[7] = __uint_as_float(zv.w & 0xffff0000u);
;     float ss = 0.f;
; #pragma unroll
;     for (int i = 0; i < 8; ++i) ss += v[i] * v[i];
; #pragma unroll
;     for (int o = 8; o >= 1; o >>= 1) ss += __shfl_xor(ss, o);
;     const float rr = rsqrtf(ss * (1.f / 128.f) + 1e-6f);
;     float y[8];
; #pragma unroll
;     for (int i = 0; i < 8; ++i) y[i] = v[i] * rr * gq[i] * z[i];
;     uint4 w; w.x = pack2(y[0], y[1]); w.y = pack2(y[2], y[3]); w.z = pack2(y[4], y[5]); w.w = pack2(y[6], y[7]);
;     *(uint4*)(p.projZ + (size_t)t * LDA_Z + 256 + lane * 8) = w;
.LBB0_86:
	v_add_u32_e32 v0, s94, v18
	v_cmp_gt_i32_e32 vcc, s51, v0
	s_waitcnt vmcnt(1)
	v_lshlrev_b32_e32 v38, 16, v10
	v_and_b32_e32 v39, 0xffff0000, v10
	v_cndmask_b32_e32 v30, v18, v0, vcc
	v_ashrrev_i32_e32 v31, 31, v30
	v_lshlrev_b64 v[32:33], 10, v[30:31]
	v_lshlrev_b64 v[30:31], 11, v[30:31]
	v_lshl_add_u64 v[32:33], v[20:21], 0, v[32:33]
	v_lshl_add_u64 v[34:35], v[22:23], 0, v[30:31]
	global_load_dwordx4 v[30:33], v[32:33], off
	s_nop 0
	global_load_dwordx4 v[34:37], v[34:35], off offset:512
	v_lshlrev_b32_e32 v10, 16, v11
	v_and_b32_e32 v11, 0xffff0000, v11
	v_pk_mul_f32 v[52:53], v[38:39], v[38:39]
	v_cmp_lt_i32_e32 vcc, s46, v0
	v_pk_mul_f32 v[50:51], v[10:11], v[10:11]
	v_mov_b32_e32 v18, v0
	v_add_f32_e32 v0, v52, v53
	v_lshlrev_b32_e32 v40, 16, v12
	v_and_b32_e32 v41, 0xffff0000, v12
	v_add_f32_e32 v0, v50, v0
	v_pk_mul_f32 v[48:49], v[40:41], v[40:41]
	v_add_f32_e32 v0, v51, v0
	v_lshlrev_b32_e32 v12, 16, v13
	v_and_b32_e32 v13, 0xffff0000, v13
	v_add_f32_e32 v0, v48, v0
	s_waitcnt vmcnt(2)
	v_lshlrev_b32_e32 v42, 16, v17
	v_and_b32_e32 v43, 0xffff0000, v17
	v_lshlrev_b32_e32 v44, 16, v16
	v_and_b32_e32 v45, 0xffff0000, v16
	v_lshlrev_b32_e32 v16, 16, v15
	v_and_b32_e32 v17, 0xffff0000, v15
	v_lshlrev_b32_e32 v46, 16, v14
	v_and_b32_e32 v47, 0xffff0000, v14
	v_pk_mul_f32 v[14:15], v[12:13], v[12:13]
	v_add_f32_e32 v0, v49, v0
	v_add_f32_e32 v0, v14, v0
	v_add_f32_e32 v0, v15, v0
	s_or_b64 s[2:3], vcc, s[2:3]
	s_nop 1
	v_add_f32_dpp v0, v0, v0 row_ror:8 row_mask:0xf bank_mask:0xf
	s_nop 1
	v_add_f32_dpp v0, v0, v0 row_ror:4 row_mask:0xf bank_mask:0xf
	s_nop 1
	v_add_f32_dpp v0, v0, v0 row_ror:2 row_mask:0xf bank_mask:0xf
	s_nop 1
	v_add_f32_dpp v0, v0, v0 row_ror:1 row_mask:0xf bank_mask:0xf
	v_fmamk_f32 v0, v0, 0x3c000000, v227
	v_mul_f32_e32 v14, 0x4b800000, v0
	v_cmp_gt_f32_e32 vcc, s14, v0
	s_nop 1
	v_cndmask_b32_e32 v0, v0, v14, vcc
	v_rsq_f32_e32 v0, v0
	s_nop 0
	v_mul_f32_e32 v14, 0x45800000, v0
	v_cndmask_b32_e32 v0, v0, v14, vcc
	v_pk_mul_f32 v[14:15], v[0:1], v[38:39] op_sel_hi:[0,1]
	v_pk_mul_f32 v[10:11], v[0:1], v[10:11] op_sel_hi:[0,1]
	v_pk_mul_f32 v[38:39], v[0:1], v[40:41] op_sel_hi:[0,1]
	v_pk_mul_f32 v[12:13], v[0:1], v[12:13] op_sel_hi:[0,1]
	v_pk_mul_f32 v[14:15], v[6:7], v[14:15]
	v_pk_mul_f32 v[10:11], v[8:9], v[10:11]
	v_pk_mul_f32 v[38:39], v[2:3], v[38:39]
	v_pk_mul_f32 v[12:13], v[4:5], v[12:13]
	v_pk_mul_f32 v[14:15], v[14:15], v[46:47]
	v_pk_mul_f32 v[16:17], v[10:11], v[16:17]
	v_pk_mul_f32 v[38:39], v[38:39], v[44:45]
	v_pk_mul_f32 v[40:41], v[12:13], v[42:43]
	v_cvt_pk_bf16_f32 v10, v14, v15
	v_cvt_pk_bf16_f32 v11, v16, v17
	v_cvt_pk_bf16_f32 v12, v38, v39
	v_cvt_pk_bf16_f32 v13, v40, v41
	global_store_dwordx4 v[24:25], v[10:13], off
	v_lshl_add_u64 v[24:25], v[24:25], 0, s[44:45]
	s_waitcnt vmcnt(1)
	v_mov_b64_e32 v[16:17], v[36:37]
	v_mov_b64_e32 v[12:13], v[32:33]
	v_mov_b64_e32 v[10:11], v[30:31]
	v_mov_b64_e32 v[14:15], v[34:35]
	s_andn2_b64 exec, exec, s[2:3]
	s_cbranch_execnz .LBB0_86
